# v4 + rwkv chunk loop rewritten: LDS staging of next chunk moved mid-loop, 1.5-chunk global prefetch, lean counter barrier
# speedup vs baseline: 1.0219x; 1.0019x over previous
; __device__ __forceinline__ float lo2f(unsigned w) { return __uint_as_float(w << 16); }
; __device__ __forceinline__ float hi2f(unsigned w) { return __uint_as_float(w & 0xffff0000u); }
; __device__ __forceinline__ void rwkv_scan_unit(CP p, int u, char* smem) {
;     ...
;   auto gload = [&](int c) {
;     const int rb = rowof(b, c * 16);
; #pragma unroll
;     for (int x = 0; x < 3; ++x) {
;       const int e = tid + x * 256, tok = e / 48, rem = e % 48, vec = rem >> 3, part = rem & 7;
;       st[x] = *reinterpret_cast<const uint4*>(RW + (size_t)(rb + tok) * 1536 + vec * 256 + h * 64 + part * 8);
;     }
;   };
;   auto lwrite = [&](int bi) {
; #pragma unroll
;     for (int x = 0; x < 3; ++x) {
;       const int e = tid + x * 256, tok = e / 48, rem = e % 48, vec = rem >> 3, part = rem & 7;
;       float* d = buf + bi * 6144 + tok * 384 + vec * 64 + part * 8;
;       *reinterpret_cast<float4*>(d) = make_float4(lo2f(st[x].x), hi2f(st[x].x), lo2f(st[x].y), hi2f(st[x].y));
;       *reinterpret_cast<float4*>(d + 4) = make_float4(lo2f(st[x].z), hi2f(st[x].z), lo2f(st[x].w), hi2f(st[x].w));
;     }
;   };
;   half_barrier(smem);
;   gload(0);
;   lwrite(0);
;   half_barrier(smem);
;   constexpr int NCH = T / 16;
;   for (int c = 0; c < NCH; ++c) {
;     if (c + 1 < NCH) gload(c + 1);
;     const float* cb = buf + (c & 1) * 6144;
;     float ykeep = 0.f;
;     float4 om = *reinterpret_cast<const float4*>(cb + j * 4);
;     float4 kk = *reinterpret_cast<const float4*>(cb + 64 + j * 4);
;     float4 bb = *reinterpret_cast<const float4*>(cb + 128 + j * 4);
;     float4 kp = *reinterpret_cast<const float4*>(cb + 192 + j * 4);
;     float4 rr = *reinterpret_cast<const float4*>(cb + 256 + j * 4);
;     float vv = cb[320 + rowv];
; #pragma unroll 2
;     for (int s = 0; s < 16; ++s) {
;       const float* sb = cb + (s + 1) * 384;
;       const float4 om_n = *reinterpret_cast<const float4*>(sb + j * 4);
;       const float4 kk_n = *reinterpret_cast<const float4*>(sb + 64 + j * 4);
;       const float4 bb_n = *reinterpret_cast<const float4*>(sb + 128 + j * 4);
;       const float4 kp_n = *reinterpret_cast<const float4*>(sb + 192 + j * 4);
;       const float4 rr_n = *reinterpret_cast<const float4*>(sb + 256 + j * 4);
;       const float vv_n = sb[320 + rowv];
;       __builtin_amdgcn_sched_barrier(0);
;       float d = s0 * kk.x + s1 * kk.y + s2 * kk.z + s3 * kk.w;
.LBB0_572:
	s_or_b64 exec, exec, s[2:3]
	s_and_b32 s12, s11, 48
	v_readlane_b32 s0, v254, 1
	v_readlane_b32 s1, v254, 2
	s_add_u32 s2, s0, s80
	s_addc_u32 s3, s1, 0
	s_lshl_b32 s4, s57, 7
	v_ashrrev_i32_e32 v17, 4, v22
	s_and_b32 s11, s4, 0xfffff800
	v_bfe_u32 v23, v22, 4, 2
	v_and_b32_e32 v76, 15, v22
	v_and_b32_e32 v22, -4, v17
	s_add_i32 s11, s11, -16
	v_add_u32_e32 v17, s12, v22
	v_lshl_add_u64 v[12:13], v[12:13], 1, s[2:3]
	s_add_u32 s4, s30, s80
	v_or_b32_e32 v48, v17, v23
	v_lshl_add_u64 v[50:51], v[12:13], 0, v[148:149]
	v_lshl_add_u64 v[12:13], v[14:15], 1, s[2:3]
	v_mov_b32_e32 v17, v149
	s_addc_u32 s5, s31, 0
	s_and_b32 s12, s37, 48
	v_lshl_add_u64 v[52:53], v[12:13], 0, v[16:17]
	v_lshl_add_u64 v[12:13], v[18:19], 1, s[2:3]
	v_mov_b32_e32 v21, v149
	v_lshl_add_u64 v[54:55], v[12:13], 0, v[20:21]
	v_add_u32_e32 v12, s12, v22
	v_ashrrev_i32_e32 v49, 31, v48
	v_or_b32_e32 v12, v12, v23
	v_mov_b32_e32 v148, v149
	v_lshlrev_b32_e32 v77, 2, v76
	v_lshl_add_u64 v[56:57], v[48:49], 1, s[4:5]
	v_lshl_add_u32 v49, v12, 2, s36
	v_lshl_add_u32 v78, v76, 4, s56
	s_mov_b32 s4, 0
	v_mov_b64_e32 v[60:61], v[148:149]
	v_mov_b64_e32 v[58:59], v[148:149]
	v_mov_b32_e32 v193, 0x20000
	v_lshl_add_u32 v193, v213, 2, v193
	v_mov_b32_e32 v195, 1
	ds_read_b32 v194, v193 offset:8
	s_add_i32 s5, s11, 16
	v_add_u32_e32 v0, s5, v63
	v_add_u32_e32 v2, s5, v65
	v_add_u32_e32 v8, s5, v66
	v_mad_i64_i32 v[0:1], s[12:13], v0, s66, v[50:51]
	v_mad_i64_i32 v[4:5], s[12:13], v2, s66, v[52:53]
	v_mad_i64_i32 v[8:9], s[12:13], v8, s66, v[54:55]
	global_load_dwordx4 v[0:3], v[0:1], off
	global_load_dwordx4 v[4:7], v[4:5], off
	global_load_dwordx4 v[8:11], v[8:9], off
	s_waitcnt lgkmcnt(0)
	v_and_b32_e32 v194, -4, v194
.Lrw_head:
	s_add_i32 s28, s4, 1
	s_bitcmp1_b32 s4, 0
	s_cselect_b32 s12, 0x6000, 0
	s_add_i32 s13, s63, s12
	v_lshl_add_u32 v78, v77, 2, s13
	v_lshl_add_u32 v79, v48, 2, s13
	ds_read_b128 v[94:97], v78 offset:256
	ds_read_b128 v[90:93], v78 offset:0
	ds_read_b128 v[102:105], v78 offset:768
	ds_read_b32 v110, v79 offset:1280
	ds_read_b128 v[98:101], v78 offset:512
	ds_read_b128 v[106:109], v78 offset:1024
	s_waitcnt lgkmcnt(5)
	v_pk_mul_f32 v[176:177], v[60:61], v[94:95]
	v_pk_fma_f32 v[176:177], v[58:59], v[96:97], v[176:177]
	ds_read_b128 v[116:119], v78 offset:1792
	s_waitcnt lgkmcnt(5)
	v_pk_fma_f32 v[180:181], v[60:61], v[90:91], v[60:61] neg_lo:[1,0,0] neg_hi:[1,0,0]
	v_add_f32_e32 v178, v176, v177
	v_pk_fma_f32 v[182:183], v[58:59], v[92:93], v[58:59] neg_lo:[1,0,0] neg_hi:[1,0,0]
	ds_read_b128 v[112:115], v78 offset:1536
	v_add_f32_dpp v178, v178, v178 quad_perm:[1,0,3,2] row_mask:0xf bank_mask:0xf bound_ctrl:1
	s_waitcnt lgkmcnt(4)
	v_pk_fma_f32 v[180:181], v[110:111], v[102:103], v[180:181] op_sel_hi:[0,1,1]
	v_pk_fma_f32 v[182:183], v[110:111], v[104:105], v[182:183] op_sel_hi:[0,1,1]
	v_add_f32_dpp v178, v178, v178 quad_perm:[2,3,0,1] row_mask:0xf bank_mask:0xf bound_ctrl:1
	ds_read_b128 v[124:127], v78 offset:2304
	ds_read_b32 v132, v79 offset:2816
	v_add_f32_dpp v178, v178, v178 row_half_mirror row_mask:0xf bank_mask:0xf bound_ctrl:1
	ds_read_b128 v[120:123], v78 offset:2048
	s_nop 0
	v_add_f32_dpp v178, v178, v178 row_mirror row_mask:0xf bank_mask:0xf bound_ctrl:1
	s_waitcnt lgkmcnt(6)
	v_pk_fma_f32 v[60:61], v[178:179], v[98:99], v[180:181] op_sel_hi:[0,1,1] neg_lo:[1,0,0] neg_hi:[1,0,0]
	v_pk_fma_f32 v[58:59], v[178:179], v[100:101], v[182:183] op_sel_hi:[0,1,1] neg_lo:[1,0,0] neg_hi:[1,0,0]
	ds_read_b128 v[128:131], v78 offset:2560
	s_waitcnt lgkmcnt(5)
	v_pk_mul_f32 v[176:177], v[60:61], v[116:117]
	v_pk_fma_f32 v[176:177], v[58:59], v[118:119], v[176:177]
	ds_read_b128 v[94:97], v78 offset:3328
	s_waitcnt lgkmcnt(5)
	v_pk_fma_f32 v[180:181], v[60:61], v[112:113], v[60:61] neg_lo:[1,0,0] neg_hi:[1,0,0]
	v_add_f32_e32 v178, v176, v177
	v_pk_fma_f32 v[182:183], v[58:59], v[114:115], v[58:59] neg_lo:[1,0,0] neg_hi:[1,0,0]
	ds_read_b128 v[90:93], v78 offset:3072
	v_add_f32_dpp v178, v178, v178 quad_perm:[1,0,3,2] row_mask:0xf bank_mask:0xf bound_ctrl:1
	s_waitcnt lgkmcnt(4)
	v_pk_fma_f32 v[180:181], v[132:133], v[124:125], v[180:181] op_sel_hi:[0,1,1]
	v_pk_fma_f32 v[182:183], v[132:133], v[126:127], v[182:183] op_sel_hi:[0,1,1]
	v_add_f32_dpp v178, v178, v178 quad_perm:[2,3,0,1] row_mask:0xf bank_mask:0xf bound_ctrl:1
	v_pk_mul_f32 v[184:185], v[60:61], v[106:107]
	v_pk_fma_f32 v[184:185], v[58:59], v[108:109], v[184:185]
	v_add_f32_dpp v178, v178, v178 row_half_mirror row_mask:0xf bank_mask:0xf bound_ctrl:1
	ds_read_b128 v[102:105], v78 offset:3840
	ds_read_b32 v110, v79 offset:4352
	v_add_f32_dpp v178, v178, v178 row_mirror row_mask:0xf bank_mask:0xf bound_ctrl:1
	v_add_f32_e32 v160, v184, v185
	ds_read_b128 v[98:101], v78 offset:3584
	s_waitcnt lgkmcnt(6)
	v_pk_fma_f32 v[60:61], v[178:179], v[120:121], v[180:181] op_sel_hi:[0,1,1] neg_lo:[1,0,0] neg_hi:[1,0,0]
	v_pk_fma_f32 v[58:59], v[178:179], v[122:123], v[182:183] op_sel_hi:[0,1,1] neg_lo:[1,0,0] neg_hi:[1,0,0]
	ds_read_b128 v[106:109], v78 offset:4096
	s_waitcnt lgkmcnt(5)
	v_pk_mul_f32 v[176:177], v[60:61], v[94:95]
	v_pk_fma_f32 v[176:177], v[58:59], v[96:97], v[176:177]
	ds_read_b128 v[116:119], v78 offset:4864
	s_waitcnt lgkmcnt(5)
	v_pk_fma_f32 v[180:181], v[60:61], v[90:91], v[60:61] neg_lo:[1,0,0] neg_hi:[1,0,0]
	v_add_f32_e32 v178, v176, v177
	v_pk_fma_f32 v[182:183], v[58:59], v[92:93], v[58:59] neg_lo:[1,0,0] neg_hi:[1,0,0]
	ds_read_b128 v[112:115], v78 offset:4608
	v_add_f32_dpp v178, v178, v178 quad_perm:[1,0,3,2] row_mask:0xf bank_mask:0xf bound_ctrl:1
	s_waitcnt lgkmcnt(4)
; __device__ __forceinline__ void rwkv_scan_unit(CP p, int u, char* smem) {
;     ...
;     for (int s = 0; s < 16; ++s) {
;       const float* sb = cb + (s + 1) * 384;
;       const float4 om_n = *reinterpret_cast<const float4*>(sb + j * 4);
;       const float4 kk_n = *reinterpret_cast<const float4*>(sb + 64 + j * 4);
;       const float4 bb_n = *reinterpret_cast<const float4*>(sb + 128 + j * 4);
;       const float4 kp_n = *reinterpret_cast<const float4*>(sb + 192 + j * 4);
;       const float4 rr_n = *reinterpret_cast<const float4*>(sb + 256 + j * 4);
;       const float vv_n = sb[320 + rowv];
;       __builtin_amdgcn_sched_barrier(0);
;       float d = s0 * kk.x + s1 * kk.y + s2 * kk.z + s3 * kk.w;
;       d = allreduce16(d);
;       const float sa = -d;
;       s0 = fmaf(-s0, om.x, s0); s1 = fmaf(-s1, om.y, s1); s2 = fmaf(-s2, om.z, s2); s3 = fmaf(-s3, om.w, s3);
;       s0 = fmaf(sa, bb.x, s0); s1 = fmaf(sa, bb.y, s1); s2 = fmaf(sa, bb.z, s2); s3 = fmaf(sa, bb.w, s3);
;       s0 = fmaf(vv, kp.x, s0); s1 = fmaf(vv, kp.y, s1); s2 = fmaf(vv, kp.z, s2); s3 = fmaf(vv, kp.w, s3);
;       float y = s0 * rr.x + s1 * rr.y + s2 * rr.z + s3 * rr.w;
;       y = allreduce16(y);
;       if (j == s) ykeep = y;
;       om = om_n; kk = kk_n; bb = bb_n; kp = kp_n; rr = rr_n; vv = vv_n;
;     }
	v_pk_fma_f32 v[180:181], v[110:111], v[102:103], v[180:181] op_sel_hi:[0,1,1]
	v_pk_fma_f32 v[182:183], v[110:111], v[104:105], v[182:183] op_sel_hi:[0,1,1]
	v_add_f32_dpp v178, v178, v178 quad_perm:[2,3,0,1] row_mask:0xf bank_mask:0xf bound_ctrl:1
	v_pk_mul_f32 v[184:185], v[60:61], v[128:129]
	v_pk_fma_f32 v[184:185], v[58:59], v[130:131], v[184:185]
	v_add_f32_dpp v178, v178, v178 row_half_mirror row_mask:0xf bank_mask:0xf bound_ctrl:1
	ds_read_b128 v[124:127], v78 offset:5376
	ds_read_b32 v132, v79 offset:5888
	v_add_f32_dpp v178, v178, v178 row_mirror row_mask:0xf bank_mask:0xf bound_ctrl:1
	v_add_f32_e32 v161, v184, v185
	ds_read_b128 v[120:123], v78 offset:5120
	s_waitcnt lgkmcnt(6)
	v_pk_fma_f32 v[60:61], v[178:179], v[98:99], v[180:181] op_sel_hi:[0,1,1] neg_lo:[1,0,0] neg_hi:[1,0,0]
	v_pk_fma_f32 v[58:59], v[178:179], v[100:101], v[182:183] op_sel_hi:[0,1,1] neg_lo:[1,0,0] neg_hi:[1,0,0]
	ds_read_b128 v[128:131], v78 offset:5632
	s_waitcnt lgkmcnt(5)
	v_pk_mul_f32 v[176:177], v[60:61], v[116:117]
	v_pk_fma_f32 v[176:177], v[58:59], v[118:119], v[176:177]
	ds_read_b128 v[94:97], v78 offset:6400
	s_waitcnt lgkmcnt(5)
	v_pk_fma_f32 v[180:181], v[60:61], v[112:113], v[60:61] neg_lo:[1,0,0] neg_hi:[1,0,0]
	v_add_f32_e32 v178, v176, v177
	v_pk_fma_f32 v[182:183], v[58:59], v[114:115], v[58:59] neg_lo:[1,0,0] neg_hi:[1,0,0]
	ds_read_b128 v[90:93], v78 offset:6144
	v_add_f32_dpp v178, v178, v178 quad_perm:[1,0,3,2] row_mask:0xf bank_mask:0xf bound_ctrl:1
	s_waitcnt lgkmcnt(4)
	v_pk_fma_f32 v[180:181], v[132:133], v[124:125], v[180:181] op_sel_hi:[0,1,1]
	v_pk_fma_f32 v[182:183], v[132:133], v[126:127], v[182:183] op_sel_hi:[0,1,1]
	v_add_f32_dpp v178, v178, v178 quad_perm:[2,3,0,1] row_mask:0xf bank_mask:0xf bound_ctrl:1
	v_pk_mul_f32 v[184:185], v[60:61], v[106:107]
	v_pk_fma_f32 v[184:185], v[58:59], v[108:109], v[184:185]
	v_add_f32_dpp v178, v178, v178 row_half_mirror row_mask:0xf bank_mask:0xf bound_ctrl:1
	ds_read_b128 v[102:105], v78 offset:6912
	ds_read_b32 v110, v79 offset:7424
	v_add_f32_dpp v178, v178, v178 row_mirror row_mask:0xf bank_mask:0xf bound_ctrl:1
	v_add_f32_e32 v162, v184, v185
	ds_read_b128 v[98:101], v78 offset:6656
	s_waitcnt lgkmcnt(6)
	v_pk_fma_f32 v[60:61], v[178:179], v[120:121], v[180:181] op_sel_hi:[0,1,1] neg_lo:[1,0,0] neg_hi:[1,0,0]
	v_pk_fma_f32 v[58:59], v[178:179], v[122:123], v[182:183] op_sel_hi:[0,1,1] neg_lo:[1,0,0] neg_hi:[1,0,0]
	ds_read_b128 v[106:109], v78 offset:7168
	s_waitcnt lgkmcnt(5)
	v_pk_mul_f32 v[176:177], v[60:61], v[94:95]
	v_pk_fma_f32 v[176:177], v[58:59], v[96:97], v[176:177]
	ds_read_b128 v[116:119], v78 offset:7936
	s_waitcnt lgkmcnt(5)
	v_pk_fma_f32 v[180:181], v[60:61], v[90:91], v[60:61] neg_lo:[1,0,0] neg_hi:[1,0,0]
	v_add_f32_e32 v178, v176, v177
	v_pk_fma_f32 v[182:183], v[58:59], v[92:93], v[58:59] neg_lo:[1,0,0] neg_hi:[1,0,0]
	ds_read_b128 v[112:115], v78 offset:7680
	v_add_f32_dpp v178, v178, v178 quad_perm:[1,0,3,2] row_mask:0xf bank_mask:0xf bound_ctrl:1
	s_waitcnt lgkmcnt(4)
	v_pk_fma_f32 v[180:181], v[110:111], v[102:103], v[180:181] op_sel_hi:[0,1,1]
	v_pk_fma_f32 v[182:183], v[110:111], v[104:105], v[182:183] op_sel_hi:[0,1,1]
	v_add_f32_dpp v178, v178, v178 quad_perm:[2,3,0,1] row_mask:0xf bank_mask:0xf bound_ctrl:1
	v_pk_mul_f32 v[184:185], v[60:61], v[128:129]
	v_pk_fma_f32 v[184:185], v[58:59], v[130:131], v[184:185]
	v_add_f32_dpp v178, v178, v178 row_half_mirror row_mask:0xf bank_mask:0xf bound_ctrl:1
	ds_read_b128 v[124:127], v78 offset:8448
	ds_read_b32 v132, v79 offset:8960
	v_add_f32_dpp v178, v178, v178 row_mirror row_mask:0xf bank_mask:0xf bound_ctrl:1
	v_add_f32_e32 v163, v184, v185
	ds_read_b128 v[120:123], v78 offset:8192
	s_waitcnt lgkmcnt(6)
	v_pk_fma_f32 v[60:61], v[178:179], v[98:99], v[180:181] op_sel_hi:[0,1,1] neg_lo:[1,0,0] neg_hi:[1,0,0]
	v_pk_fma_f32 v[58:59], v[178:179], v[100:101], v[182:183] op_sel_hi:[0,1,1] neg_lo:[1,0,0] neg_hi:[1,0,0]
	ds_read_b128 v[128:131], v78 offset:8704
	s_waitcnt lgkmcnt(5)
	v_pk_mul_f32 v[176:177], v[60:61], v[116:117]
	v_pk_fma_f32 v[176:177], v[58:59], v[118:119], v[176:177]
	ds_read_b128 v[94:97], v78 offset:9472
	s_waitcnt lgkmcnt(5)
	v_pk_fma_f32 v[180:181], v[60:61], v[112:113], v[60:61] neg_lo:[1,0,0] neg_hi:[1,0,0]
	v_add_f32_e32 v178, v176, v177
	v_pk_fma_f32 v[182:183], v[58:59], v[114:115], v[58:59] neg_lo:[1,0,0] neg_hi:[1,0,0]
	ds_read_b128 v[90:93], v78 offset:9216
	v_add_f32_dpp v178, v178, v178 quad_perm:[1,0,3,2] row_mask:0xf bank_mask:0xf bound_ctrl:1
	s_waitcnt lgkmcnt(4)
	v_pk_fma_f32 v[180:181], v[132:133], v[124:125], v[180:181] op_sel_hi:[0,1,1]
	v_pk_fma_f32 v[182:183], v[132:133], v[126:127], v[182:183] op_sel_hi:[0,1,1]
	v_add_f32_dpp v178, v178, v178 quad_perm:[2,3,0,1] row_mask:0xf bank_mask:0xf bound_ctrl:1
	v_pk_mul_f32 v[184:185], v[60:61], v[106:107]
	v_pk_fma_f32 v[184:185], v[58:59], v[108:109], v[184:185]
	v_add_f32_dpp v178, v178, v178 row_half_mirror row_mask:0xf bank_mask:0xf bound_ctrl:1
	ds_read_b128 v[102:105], v78 offset:9984
	ds_read_b32 v110, v79 offset:10496
	v_add_f32_dpp v178, v178, v178 row_mirror row_mask:0xf bank_mask:0xf bound_ctrl:1
	v_add_f32_e32 v164, v184, v185
	ds_read_b128 v[98:101], v78 offset:9728
	s_waitcnt lgkmcnt(6)
	v_pk_fma_f32 v[60:61], v[178:179], v[120:121], v[180:181] op_sel_hi:[0,1,1] neg_lo:[1,0,0] neg_hi:[1,0,0]
	v_pk_fma_f32 v[58:59], v[178:179], v[122:123], v[182:183] op_sel_hi:[0,1,1] neg_lo:[1,0,0] neg_hi:[1,0,0]
	ds_read_b128 v[106:109], v78 offset:10240
	s_waitcnt lgkmcnt(5)
	v_pk_mul_f32 v[176:177], v[60:61], v[94:95]
	v_pk_fma_f32 v[176:177], v[58:59], v[96:97], v[176:177]
	ds_read_b128 v[116:119], v78 offset:11008
	s_waitcnt lgkmcnt(5)
; __device__ __forceinline__ float lo2f(unsigned w) { return __uint_as_float(w << 16); }
; __device__ __forceinline__ float hi2f(unsigned w) { return __uint_as_float(w & 0xffff0000u); }
; __device__ __forceinline__ void rwkv_scan_unit(CP p, int u, char* smem) {
;     ...
;   auto gload = [&](int c) {
;     const int rb = rowof(b, c * 16);
; #pragma unroll
;     for (int x = 0; x < 3; ++x) {
;       const int e = tid + x * 256, tok = e / 48, rem = e % 48, vec = rem >> 3, part = rem & 7;
;       st[x] = *reinterpret_cast<const uint4*>(RW + (size_t)(rb + tok) * 1536 + vec * 256 + h * 64 + part * 8);
;     }
;   };
;   auto lwrite = [&](int bi) {
; #pragma unroll
;     for (int x = 0; x < 3; ++x) {
;       const int e = tid + x * 256, tok = e / 48, rem = e % 48, vec = rem >> 3, part = rem & 7;
;       float* d = buf + bi * 6144 + tok * 384 + vec * 64 + part * 8;
;       *reinterpret_cast<float4*>(d) = make_float4(lo2f(st[x].x), hi2f(st[x].x), lo2f(st[x].y), hi2f(st[x].y));
;       *reinterpret_cast<float4*>(d + 4) = make_float4(lo2f(st[x].z), hi2f(st[x].z), lo2f(st[x].w), hi2f(st[x].w));
;     }
;     ...
;     for (int s = 0; s < 16; ++s) {
;       const float* sb = cb + (s + 1) * 384;
;       const float4 om_n = *reinterpret_cast<const float4*>(sb + j * 4);
;       const float4 kk_n = *reinterpret_cast<const float4*>(sb + 64 + j * 4);
;       const float4 bb_n = *reinterpret_cast<const float4*>(sb + 128 + j * 4);
;       const float4 kp_n = *reinterpret_cast<const float4*>(sb + 192 + j * 4);
;       const float4 rr_n = *reinterpret_cast<const float4*>(sb + 256 + j * 4);
;       const float vv_n = sb[320 + rowv];
;       __builtin_amdgcn_sched_barrier(0);
;       float d = s0 * kk.x + s1 * kk.y + s2 * kk.z + s3 * kk.w;
;       d = allreduce16(d);
;       const float sa = -d;
;       s0 = fmaf(-s0, om.x, s0); s1 = fmaf(-s1, om.y, s1); s2 = fmaf(-s2, om.z, s2); s3 = fmaf(-s3, om.w, s3);
;       s0 = fmaf(sa, bb.x, s0); s1 = fmaf(sa, bb.y, s1); s2 = fmaf(sa, bb.z, s2); s3 = fmaf(sa, bb.w, s3);
;       s0 = fmaf(vv, kp.x, s0); s1 = fmaf(vv, kp.y, s1); s2 = fmaf(vv, kp.z, s2); s3 = fmaf(vv, kp.w, s3);
;       float y = s0 * rr.x + s1 * rr.y + s2 * rr.z + s3 * rr.w;
;       y = allreduce16(y);
	v_pk_fma_f32 v[180:181], v[60:61], v[90:91], v[60:61] neg_lo:[1,0,0] neg_hi:[1,0,0]
	v_add_f32_e32 v178, v176, v177
	v_pk_fma_f32 v[182:183], v[58:59], v[92:93], v[58:59] neg_lo:[1,0,0] neg_hi:[1,0,0]
	ds_read_b128 v[112:115], v78 offset:10752
	v_add_f32_dpp v178, v178, v178 quad_perm:[1,0,3,2] row_mask:0xf bank_mask:0xf bound_ctrl:1
	s_waitcnt lgkmcnt(4)
	v_pk_fma_f32 v[180:181], v[110:111], v[102:103], v[180:181] op_sel_hi:[0,1,1]
	v_pk_fma_f32 v[182:183], v[110:111], v[104:105], v[182:183] op_sel_hi:[0,1,1]
	v_add_f32_dpp v178, v178, v178 quad_perm:[2,3,0,1] row_mask:0xf bank_mask:0xf bound_ctrl:1
	v_pk_mul_f32 v[184:185], v[60:61], v[128:129]
	v_pk_fma_f32 v[184:185], v[58:59], v[130:131], v[184:185]
	v_add_f32_dpp v178, v178, v178 row_half_mirror row_mask:0xf bank_mask:0xf bound_ctrl:1
	ds_read_b128 v[124:127], v78 offset:11520
	ds_read_b32 v132, v79 offset:12032
	v_add_f32_dpp v178, v178, v178 row_mirror row_mask:0xf bank_mask:0xf bound_ctrl:1
	v_add_f32_e32 v165, v184, v185
	ds_read_b128 v[120:123], v78 offset:11264
	s_waitcnt lgkmcnt(6)
	v_pk_fma_f32 v[60:61], v[178:179], v[98:99], v[180:181] op_sel_hi:[0,1,1] neg_lo:[1,0,0] neg_hi:[1,0,0]
	v_pk_fma_f32 v[58:59], v[178:179], v[100:101], v[182:183] op_sel_hi:[0,1,1] neg_lo:[1,0,0] neg_hi:[1,0,0]
	ds_read_b128 v[128:131], v78 offset:11776
	s_waitcnt lgkmcnt(5)
	v_pk_mul_f32 v[176:177], v[60:61], v[116:117]
	v_pk_fma_f32 v[176:177], v[58:59], v[118:119], v[176:177]
	ds_read_b128 v[94:97], v78 offset:12544
	s_waitcnt lgkmcnt(5)
	v_pk_fma_f32 v[180:181], v[60:61], v[112:113], v[60:61] neg_lo:[1,0,0] neg_hi:[1,0,0]
	v_add_f32_e32 v178, v176, v177
	v_pk_fma_f32 v[182:183], v[58:59], v[114:115], v[58:59] neg_lo:[1,0,0] neg_hi:[1,0,0]
	ds_read_b128 v[90:93], v78 offset:12288
	v_add_f32_dpp v178, v178, v178 quad_perm:[1,0,3,2] row_mask:0xf bank_mask:0xf bound_ctrl:1
	s_waitcnt lgkmcnt(4)
	v_pk_fma_f32 v[180:181], v[132:133], v[124:125], v[180:181] op_sel_hi:[0,1,1]
	v_pk_fma_f32 v[182:183], v[132:133], v[126:127], v[182:183] op_sel_hi:[0,1,1]
	v_add_f32_dpp v178, v178, v178 quad_perm:[2,3,0,1] row_mask:0xf bank_mask:0xf bound_ctrl:1
	v_pk_mul_f32 v[184:185], v[60:61], v[106:107]
	v_pk_fma_f32 v[184:185], v[58:59], v[108:109], v[184:185]
	v_add_f32_dpp v178, v178, v178 row_half_mirror row_mask:0xf bank_mask:0xf bound_ctrl:1
	ds_read_b128 v[102:105], v78 offset:13056
	ds_read_b32 v110, v79 offset:13568
	v_add_f32_dpp v178, v178, v178 row_mirror row_mask:0xf bank_mask:0xf bound_ctrl:1
	v_add_f32_e32 v166, v184, v185
	ds_read_b128 v[98:101], v78 offset:12800
	s_waitcnt lgkmcnt(6)
	v_pk_fma_f32 v[60:61], v[178:179], v[120:121], v[180:181] op_sel_hi:[0,1,1] neg_lo:[1,0,0] neg_hi:[1,0,0]
	v_pk_fma_f32 v[58:59], v[178:179], v[122:123], v[182:183] op_sel_hi:[0,1,1] neg_lo:[1,0,0] neg_hi:[1,0,0]
	ds_read_b128 v[106:109], v78 offset:13312
	s_waitcnt vmcnt(0)
	s_bitcmp1_b32 s28, 0
	s_cselect_b32 s2, 0x6000, 0
	s_add_i32 s2, s63, s2
	v_lshl_add_u32 v12, v67, 2, s2
	v_add3_u32 v18, v12, v68, v69
	v_lshlrev_b32_e32 v12, 16, v0
	v_and_b32_e32 v13, 0xffff0000, v0
	v_lshlrev_b32_e32 v14, 16, v1
	v_and_b32_e32 v15, 0xffff0000, v1
	ds_write_b128 v18, v[12:15]
	v_lshlrev_b32_e32 v12, 16, v2
	v_and_b32_e32 v13, 0xffff0000, v2
	v_lshlrev_b32_e32 v14, 16, v3
	v_and_b32_e32 v15, 0xffff0000, v3
	ds_write_b128 v18, v[12:15] offset:16
	v_lshl_add_u32 v12, v70, 2, s2
	v_add3_u32 v18, v12, v71, v72
	v_lshlrev_b32_e32 v12, 16, v4
	v_and_b32_e32 v13, 0xffff0000, v4
	v_lshlrev_b32_e32 v14, 16, v5
	v_and_b32_e32 v15, 0xffff0000, v5
	ds_write_b128 v18, v[12:15]
	v_lshlrev_b32_e32 v12, 16, v6
	v_and_b32_e32 v13, 0xffff0000, v6
	v_lshlrev_b32_e32 v14, 16, v7
	v_and_b32_e32 v15, 0xffff0000, v7
	ds_write_b128 v18, v[12:15] offset:16
	v_lshl_add_u32 v12, v73, 2, s2
	v_add3_u32 v18, v12, v74, v75
	v_lshlrev_b32_e32 v12, 16, v8
	v_and_b32_e32 v13, 0xffff0000, v8
	v_lshlrev_b32_e32 v14, 16, v9
	v_and_b32_e32 v15, 0xffff0000, v9
	ds_write_b128 v18, v[12:15]
	v_lshlrev_b32_e32 v12, 16, v10
	v_and_b32_e32 v13, 0xffff0000, v10
	v_lshlrev_b32_e32 v14, 16, v11
	v_and_b32_e32 v15, 0xffff0000, v11
	ds_write_b128 v18, v[12:15] offset:16
	s_cmpk_gt_i32 s4, 0x7e
	s_cbranch_scc1 .Lrw_skipgl
	s_add_i32 s5, s4, 2
	s_lshl_b32 s5, s5, 4
	s_add_i32 s5, s5, s11
	v_add_u32_e32 v0, s5, v63
	v_add_u32_e32 v2, s5, v65
	v_add_u32_e32 v8, s5, v66
	v_mad_i64_i32 v[0:1], s[12:13], v0, s66, v[50:51]
	v_mad_i64_i32 v[4:5], s[12:13], v2, s66, v[52:53]
	v_mad_i64_i32 v[8:9], s[12:13], v8, s66, v[54:55]
	global_load_dwordx4 v[0:3], v[0:1], off
	global_load_dwordx4 v[4:7], v[4:5], off
	global_load_dwordx4 v[8:11], v[8:9], off
; __device__ __forceinline__ void rwkv_scan_unit(CP p, int u, char* smem) {
;     ...
;     for (int s = 0; s < 16; ++s) {
;       const float* sb = cb + (s + 1) * 384;
;       const float4 om_n = *reinterpret_cast<const float4*>(sb + j * 4);
;       const float4 kk_n = *reinterpret_cast<const float4*>(sb + 64 + j * 4);
;       const float4 bb_n = *reinterpret_cast<const float4*>(sb + 128 + j * 4);
;       const float4 kp_n = *reinterpret_cast<const float4*>(sb + 192 + j * 4);
;       const float4 rr_n = *reinterpret_cast<const float4*>(sb + 256 + j * 4);
;       const float vv_n = sb[320 + rowv];
;       __builtin_amdgcn_sched_barrier(0);
;       float d = s0 * kk.x + s1 * kk.y + s2 * kk.z + s3 * kk.w;
;       d = allreduce16(d);
;       const float sa = -d;
;       s0 = fmaf(-s0, om.x, s0); s1 = fmaf(-s1, om.y, s1); s2 = fmaf(-s2, om.z, s2); s3 = fmaf(-s3, om.w, s3);
;       s0 = fmaf(sa, bb.x, s0); s1 = fmaf(sa, bb.y, s1); s2 = fmaf(sa, bb.z, s2); s3 = fmaf(sa, bb.w, s3);
;       s0 = fmaf(vv, kp.x, s0); s1 = fmaf(vv, kp.y, s1); s2 = fmaf(vv, kp.z, s2); s3 = fmaf(vv, kp.w, s3);
;       float y = s0 * rr.x + s1 * rr.y + s2 * rr.z + s3 * rr.w;
;       y = allreduce16(y);
;       if (j == s) ykeep = y;
;       om = om_n; kk = kk_n; bb = bb_n; kp = kp_n; rr = rr_n; vv = vv_n;
;     }
.Lrw_skipgl:
	s_waitcnt lgkmcnt(11)
	v_pk_mul_f32 v[176:177], v[60:61], v[94:95]
	v_pk_fma_f32 v[176:177], v[58:59], v[96:97], v[176:177]
	ds_read_b128 v[116:119], v78 offset:14080
	s_waitcnt lgkmcnt(11)
	v_pk_fma_f32 v[180:181], v[60:61], v[90:91], v[60:61] neg_lo:[1,0,0] neg_hi:[1,0,0]
	v_add_f32_e32 v178, v176, v177
	v_pk_fma_f32 v[182:183], v[58:59], v[92:93], v[58:59] neg_lo:[1,0,0] neg_hi:[1,0,0]
	ds_read_b128 v[112:115], v78 offset:13824
	v_add_f32_dpp v178, v178, v178 quad_perm:[1,0,3,2] row_mask:0xf bank_mask:0xf bound_ctrl:1
	s_waitcnt lgkmcnt(10)
	v_pk_fma_f32 v[180:181], v[110:111], v[102:103], v[180:181] op_sel_hi:[0,1,1]
	v_pk_fma_f32 v[182:183], v[110:111], v[104:105], v[182:183] op_sel_hi:[0,1,1]
	v_add_f32_dpp v178, v178, v178 quad_perm:[2,3,0,1] row_mask:0xf bank_mask:0xf bound_ctrl:1
	v_pk_mul_f32 v[184:185], v[60:61], v[128:129]
	v_pk_fma_f32 v[184:185], v[58:59], v[130:131], v[184:185]
	v_add_f32_dpp v178, v178, v178 row_half_mirror row_mask:0xf bank_mask:0xf bound_ctrl:1
	ds_read_b128 v[124:127], v78 offset:14592
	ds_read_b32 v132, v79 offset:15104
	v_add_f32_dpp v178, v178, v178 row_mirror row_mask:0xf bank_mask:0xf bound_ctrl:1
	v_add_f32_e32 v167, v184, v185
	ds_read_b128 v[120:123], v78 offset:14336
	s_waitcnt lgkmcnt(12)
	v_pk_fma_f32 v[60:61], v[178:179], v[98:99], v[180:181] op_sel_hi:[0,1,1] neg_lo:[1,0,0] neg_hi:[1,0,0]
	v_pk_fma_f32 v[58:59], v[178:179], v[100:101], v[182:183] op_sel_hi:[0,1,1] neg_lo:[1,0,0] neg_hi:[1,0,0]
	ds_read_b128 v[128:131], v78 offset:14848
	s_waitcnt lgkmcnt(5)
	v_pk_mul_f32 v[176:177], v[60:61], v[116:117]
	v_pk_fma_f32 v[176:177], v[58:59], v[118:119], v[176:177]
	ds_read_b128 v[94:97], v78 offset:15616
	s_waitcnt lgkmcnt(5)
	v_pk_fma_f32 v[180:181], v[60:61], v[112:113], v[60:61] neg_lo:[1,0,0] neg_hi:[1,0,0]
	v_add_f32_e32 v178, v176, v177
	v_pk_fma_f32 v[182:183], v[58:59], v[114:115], v[58:59] neg_lo:[1,0,0] neg_hi:[1,0,0]
	ds_read_b128 v[90:93], v78 offset:15360
	v_add_f32_dpp v178, v178, v178 quad_perm:[1,0,3,2] row_mask:0xf bank_mask:0xf bound_ctrl:1
	s_waitcnt lgkmcnt(4)
	v_pk_fma_f32 v[180:181], v[132:133], v[124:125], v[180:181] op_sel_hi:[0,1,1]
	v_pk_fma_f32 v[182:183], v[132:133], v[126:127], v[182:183] op_sel_hi:[0,1,1]
	v_add_f32_dpp v178, v178, v178 quad_perm:[2,3,0,1] row_mask:0xf bank_mask:0xf bound_ctrl:1
	v_pk_mul_f32 v[184:185], v[60:61], v[106:107]
	v_pk_fma_f32 v[184:185], v[58:59], v[108:109], v[184:185]
	v_add_f32_dpp v178, v178, v178 row_half_mirror row_mask:0xf bank_mask:0xf bound_ctrl:1
	ds_read_b128 v[102:105], v78 offset:16128
	ds_read_b32 v110, v79 offset:16640
	v_add_f32_dpp v178, v178, v178 row_mirror row_mask:0xf bank_mask:0xf bound_ctrl:1
	v_add_f32_e32 v168, v184, v185
	ds_read_b128 v[98:101], v78 offset:15872
	s_waitcnt lgkmcnt(6)
	v_pk_fma_f32 v[60:61], v[178:179], v[120:121], v[180:181] op_sel_hi:[0,1,1] neg_lo:[1,0,0] neg_hi:[1,0,0]
	v_pk_fma_f32 v[58:59], v[178:179], v[122:123], v[182:183] op_sel_hi:[0,1,1] neg_lo:[1,0,0] neg_hi:[1,0,0]
	ds_read_b128 v[106:109], v78 offset:16384
	s_waitcnt lgkmcnt(5)
	v_pk_mul_f32 v[176:177], v[60:61], v[94:95]
	v_pk_fma_f32 v[176:177], v[58:59], v[96:97], v[176:177]
	ds_read_b128 v[116:119], v78 offset:17152
	s_waitcnt lgkmcnt(5)
	v_pk_fma_f32 v[180:181], v[60:61], v[90:91], v[60:61] neg_lo:[1,0,0] neg_hi:[1,0,0]
	v_add_f32_e32 v178, v176, v177
	v_pk_fma_f32 v[182:183], v[58:59], v[92:93], v[58:59] neg_lo:[1,0,0] neg_hi:[1,0,0]
	ds_read_b128 v[112:115], v78 offset:16896
	v_add_f32_dpp v178, v178, v178 quad_perm:[1,0,3,2] row_mask:0xf bank_mask:0xf bound_ctrl:1
	s_waitcnt lgkmcnt(4)
	v_pk_fma_f32 v[180:181], v[110:111], v[102:103], v[180:181] op_sel_hi:[0,1,1]
	v_pk_fma_f32 v[182:183], v[110:111], v[104:105], v[182:183] op_sel_hi:[0,1,1]
	v_add_f32_dpp v178, v178, v178 quad_perm:[2,3,0,1] row_mask:0xf bank_mask:0xf bound_ctrl:1
	v_pk_mul_f32 v[184:185], v[60:61], v[128:129]
	v_pk_fma_f32 v[184:185], v[58:59], v[130:131], v[184:185]
	v_add_f32_dpp v178, v178, v178 row_half_mirror row_mask:0xf bank_mask:0xf bound_ctrl:1
	ds_read_b128 v[124:127], v78 offset:17664
	ds_read_b32 v132, v79 offset:18176
	v_add_f32_dpp v178, v178, v178 row_mirror row_mask:0xf bank_mask:0xf bound_ctrl:1
	v_add_f32_e32 v169, v184, v185
	ds_read_b128 v[120:123], v78 offset:17408
	s_waitcnt lgkmcnt(6)
	v_pk_fma_f32 v[60:61], v[178:179], v[98:99], v[180:181] op_sel_hi:[0,1,1] neg_lo:[1,0,0] neg_hi:[1,0,0]
	v_pk_fma_f32 v[58:59], v[178:179], v[100:101], v[182:183] op_sel_hi:[0,1,1] neg_lo:[1,0,0] neg_hi:[1,0,0]
	ds_read_b128 v[128:131], v78 offset:17920
	s_waitcnt lgkmcnt(5)
	v_pk_mul_f32 v[176:177], v[60:61], v[116:117]
	v_pk_fma_f32 v[176:177], v[58:59], v[118:119], v[176:177]
	ds_read_b128 v[94:97], v78 offset:18688
	s_waitcnt lgkmcnt(5)
	v_pk_fma_f32 v[180:181], v[60:61], v[112:113], v[60:61] neg_lo:[1,0,0] neg_hi:[1,0,0]
	v_add_f32_e32 v178, v176, v177
	v_pk_fma_f32 v[182:183], v[58:59], v[114:115], v[58:59] neg_lo:[1,0,0] neg_hi:[1,0,0]
	ds_read_b128 v[90:93], v78 offset:18432
	v_add_f32_dpp v178, v178, v178 quad_perm:[1,0,3,2] row_mask:0xf bank_mask:0xf bound_ctrl:1
	s_waitcnt lgkmcnt(4)
	v_pk_fma_f32 v[180:181], v[132:133], v[124:125], v[180:181] op_sel_hi:[0,1,1]
	v_pk_fma_f32 v[182:183], v[132:133], v[126:127], v[182:183] op_sel_hi:[0,1,1]
	v_add_f32_dpp v178, v178, v178 quad_perm:[2,3,0,1] row_mask:0xf bank_mask:0xf bound_ctrl:1
	v_pk_mul_f32 v[184:185], v[60:61], v[106:107]
	v_pk_fma_f32 v[184:185], v[58:59], v[108:109], v[184:185]
	v_add_f32_dpp v178, v178, v178 row_half_mirror row_mask:0xf bank_mask:0xf bound_ctrl:1
	ds_read_b128 v[102:105], v78 offset:19200
	ds_read_b32 v110, v79 offset:19712
	v_add_f32_dpp v178, v178, v178 row_mirror row_mask:0xf bank_mask:0xf bound_ctrl:1
	v_add_f32_e32 v170, v184, v185
	ds_read_b128 v[98:101], v78 offset:18944
	s_waitcnt lgkmcnt(6)
; __device__ __forceinline__ void rwkv_scan_unit(CP p, int u, char* smem) {
;     ...
;     for (int s = 0; s < 16; ++s) {
;       const float* sb = cb + (s + 1) * 384;
;       const float4 om_n = *reinterpret_cast<const float4*>(sb + j * 4);
;       const float4 kk_n = *reinterpret_cast<const float4*>(sb + 64 + j * 4);
;       const float4 bb_n = *reinterpret_cast<const float4*>(sb + 128 + j * 4);
;       const float4 kp_n = *reinterpret_cast<const float4*>(sb + 192 + j * 4);
;       const float4 rr_n = *reinterpret_cast<const float4*>(sb + 256 + j * 4);
;       const float vv_n = sb[320 + rowv];
;       __builtin_amdgcn_sched_barrier(0);
;       float d = s0 * kk.x + s1 * kk.y + s2 * kk.z + s3 * kk.w;
;       d = allreduce16(d);
;       const float sa = -d;
;       s0 = fmaf(-s0, om.x, s0); s1 = fmaf(-s1, om.y, s1); s2 = fmaf(-s2, om.z, s2); s3 = fmaf(-s3, om.w, s3);
;       s0 = fmaf(sa, bb.x, s0); s1 = fmaf(sa, bb.y, s1); s2 = fmaf(sa, bb.z, s2); s3 = fmaf(sa, bb.w, s3);
;       s0 = fmaf(vv, kp.x, s0); s1 = fmaf(vv, kp.y, s1); s2 = fmaf(vv, kp.z, s2); s3 = fmaf(vv, kp.w, s3);
;       float y = s0 * rr.x + s1 * rr.y + s2 * rr.z + s3 * rr.w;
;       y = allreduce16(y);
;       if (j == s) ykeep = y;
;       om = om_n; kk = kk_n; bb = bb_n; kp = kp_n; rr = rr_n; vv = vv_n;
;     }
	v_pk_fma_f32 v[60:61], v[178:179], v[120:121], v[180:181] op_sel_hi:[0,1,1] neg_lo:[1,0,0] neg_hi:[1,0,0]
	v_pk_fma_f32 v[58:59], v[178:179], v[122:123], v[182:183] op_sel_hi:[0,1,1] neg_lo:[1,0,0] neg_hi:[1,0,0]
	ds_read_b128 v[106:109], v78 offset:19456
	s_waitcnt lgkmcnt(5)
	v_pk_mul_f32 v[176:177], v[60:61], v[94:95]
	v_pk_fma_f32 v[176:177], v[58:59], v[96:97], v[176:177]
	ds_read_b128 v[116:119], v78 offset:20224
	s_waitcnt lgkmcnt(5)
	v_pk_fma_f32 v[180:181], v[60:61], v[90:91], v[60:61] neg_lo:[1,0,0] neg_hi:[1,0,0]
	v_add_f32_e32 v178, v176, v177
	v_pk_fma_f32 v[182:183], v[58:59], v[92:93], v[58:59] neg_lo:[1,0,0] neg_hi:[1,0,0]
	ds_read_b128 v[112:115], v78 offset:19968
	v_add_f32_dpp v178, v178, v178 quad_perm:[1,0,3,2] row_mask:0xf bank_mask:0xf bound_ctrl:1
	s_waitcnt lgkmcnt(4)
	v_pk_fma_f32 v[180:181], v[110:111], v[102:103], v[180:181] op_sel_hi:[0,1,1]
	v_pk_fma_f32 v[182:183], v[110:111], v[104:105], v[182:183] op_sel_hi:[0,1,1]
	v_add_f32_dpp v178, v178, v178 quad_perm:[2,3,0,1] row_mask:0xf bank_mask:0xf bound_ctrl:1
	v_pk_mul_f32 v[184:185], v[60:61], v[128:129]
	v_pk_fma_f32 v[184:185], v[58:59], v[130:131], v[184:185]
	v_add_f32_dpp v178, v178, v178 row_half_mirror row_mask:0xf bank_mask:0xf bound_ctrl:1
	ds_read_b128 v[124:127], v78 offset:20736
	ds_read_b32 v132, v79 offset:21248
	v_add_f32_dpp v178, v178, v178 row_mirror row_mask:0xf bank_mask:0xf bound_ctrl:1
	v_add_f32_e32 v171, v184, v185
	ds_read_b128 v[120:123], v78 offset:20480
	s_waitcnt lgkmcnt(6)
	v_pk_fma_f32 v[60:61], v[178:179], v[98:99], v[180:181] op_sel_hi:[0,1,1] neg_lo:[1,0,0] neg_hi:[1,0,0]
	v_pk_fma_f32 v[58:59], v[178:179], v[100:101], v[182:183] op_sel_hi:[0,1,1] neg_lo:[1,0,0] neg_hi:[1,0,0]
	ds_read_b128 v[128:131], v78 offset:20992
	s_waitcnt lgkmcnt(5)
	v_pk_mul_f32 v[176:177], v[60:61], v[116:117]
	v_pk_fma_f32 v[176:177], v[58:59], v[118:119], v[176:177]
	ds_read_b128 v[94:97], v78 offset:21760
	s_waitcnt lgkmcnt(5)
	v_pk_fma_f32 v[180:181], v[60:61], v[112:113], v[60:61] neg_lo:[1,0,0] neg_hi:[1,0,0]
	v_add_f32_e32 v178, v176, v177
	v_pk_fma_f32 v[182:183], v[58:59], v[114:115], v[58:59] neg_lo:[1,0,0] neg_hi:[1,0,0]
	ds_read_b128 v[90:93], v78 offset:21504
	v_add_f32_dpp v178, v178, v178 quad_perm:[1,0,3,2] row_mask:0xf bank_mask:0xf bound_ctrl:1
	s_waitcnt lgkmcnt(4)
	v_pk_fma_f32 v[180:181], v[132:133], v[124:125], v[180:181] op_sel_hi:[0,1,1]
	v_pk_fma_f32 v[182:183], v[132:133], v[126:127], v[182:183] op_sel_hi:[0,1,1]
	v_add_f32_dpp v178, v178, v178 quad_perm:[2,3,0,1] row_mask:0xf bank_mask:0xf bound_ctrl:1
	v_pk_mul_f32 v[184:185], v[60:61], v[106:107]
	v_pk_fma_f32 v[184:185], v[58:59], v[108:109], v[184:185]
	v_add_f32_dpp v178, v178, v178 row_half_mirror row_mask:0xf bank_mask:0xf bound_ctrl:1
	ds_read_b128 v[102:105], v78 offset:22272
	ds_read_b32 v110, v79 offset:22784
	v_add_f32_dpp v178, v178, v178 row_mirror row_mask:0xf bank_mask:0xf bound_ctrl:1
	v_add_f32_e32 v172, v184, v185
	ds_read_b128 v[98:101], v78 offset:22016
	s_waitcnt lgkmcnt(6)
	v_pk_fma_f32 v[60:61], v[178:179], v[120:121], v[180:181] op_sel_hi:[0,1,1] neg_lo:[1,0,0] neg_hi:[1,0,0]
	v_pk_fma_f32 v[58:59], v[178:179], v[122:123], v[182:183] op_sel_hi:[0,1,1] neg_lo:[1,0,0] neg_hi:[1,0,0]
	ds_read_b128 v[106:109], v78 offset:22528
	s_waitcnt lgkmcnt(5)
	v_pk_mul_f32 v[176:177], v[60:61], v[94:95]
	v_pk_fma_f32 v[176:177], v[58:59], v[96:97], v[176:177]
	ds_read_b128 v[116:119], v78 offset:23296
	s_waitcnt lgkmcnt(5)
	v_pk_fma_f32 v[180:181], v[60:61], v[90:91], v[60:61] neg_lo:[1,0,0] neg_hi:[1,0,0]
	v_add_f32_e32 v178, v176, v177
	v_pk_fma_f32 v[182:183], v[58:59], v[92:93], v[58:59] neg_lo:[1,0,0] neg_hi:[1,0,0]
	ds_read_b128 v[112:115], v78 offset:23040
	v_add_f32_dpp v178, v178, v178 quad_perm:[1,0,3,2] row_mask:0xf bank_mask:0xf bound_ctrl:1
	s_waitcnt lgkmcnt(4)
	v_pk_fma_f32 v[180:181], v[110:111], v[102:103], v[180:181] op_sel_hi:[0,1,1]
	v_pk_fma_f32 v[182:183], v[110:111], v[104:105], v[182:183] op_sel_hi:[0,1,1]
	v_add_f32_dpp v178, v178, v178 quad_perm:[2,3,0,1] row_mask:0xf bank_mask:0xf bound_ctrl:1
	v_pk_mul_f32 v[184:185], v[60:61], v[128:129]
	v_pk_fma_f32 v[184:185], v[58:59], v[130:131], v[184:185]
	v_add_f32_dpp v178, v178, v178 row_half_mirror row_mask:0xf bank_mask:0xf bound_ctrl:1
	ds_read_b128 v[124:127], v78 offset:23808
	ds_read_b32 v132, v79 offset:24320
	v_add_f32_dpp v178, v178, v178 row_mirror row_mask:0xf bank_mask:0xf bound_ctrl:1
	v_add_f32_e32 v173, v184, v185
	ds_read_b128 v[120:123], v78 offset:23552
	s_waitcnt lgkmcnt(6)
	v_pk_fma_f32 v[60:61], v[178:179], v[98:99], v[180:181] op_sel_hi:[0,1,1] neg_lo:[1,0,0] neg_hi:[1,0,0]
	v_pk_fma_f32 v[58:59], v[178:179], v[100:101], v[182:183] op_sel_hi:[0,1,1] neg_lo:[1,0,0] neg_hi:[1,0,0]
	ds_read_b128 v[128:131], v78 offset:24064
	s_waitcnt lgkmcnt(5)
; __device__ __forceinline__ bf16_t f2bf(float f) { return (bf16_t)(pack2(f, 0.f) & 0xffffu); }
; __device__ __forceinline__ int tidx() { int t = threadIdx.x & 255; asm volatile("" : "+v"(t)); return t; }
; __device__ __forceinline__ int half_id() { int t = (int)(threadIdx.x >> 8); asm volatile("" : "+v"(t)); return __builtin_amdgcn_readfirstlane(t); }
; #define LAS3 __attribute__((address_space(3)))
; __device__ __forceinline__ void half_barrier(char* smem_half) {
;   const int h = half_id();
;   LAS3 unsigned* cnt = (LAS3 unsigned*)(smem_half + (2 - h) * 65536 + 8 + h * 4);
;   asm volatile("s_waitcnt lgkmcnt(0)" ::: "memory");
;   if ((tidx() & 63) == 0) {
;     const unsigned old = __hip_atomic_fetch_add(cnt, 1u, __ATOMIC_RELAXED, __HIP_MEMORY_SCOPE_WORKGROUP);
;     const unsigned target = (old & ~3u) + 4u;
;     while (__hip_atomic_load(cnt, __ATOMIC_RELAXED, __HIP_MEMORY_SCOPE_WORKGROUP) < target) __builtin_amdgcn_s_sleep(1);
;   }
; __device__ __forceinline__ void rwkv_scan_unit(CP p, int u, char* smem) {
;     ...
;       float d = s0 * kk.x + s1 * kk.y + s2 * kk.z + s3 * kk.w;
;       d = allreduce16(d);
;       const float sa = -d;
;       s0 = fmaf(-s0, om.x, s0); s1 = fmaf(-s1, om.y, s1); s2 = fmaf(-s2, om.z, s2); s3 = fmaf(-s3, om.w, s3);
;       s0 = fmaf(sa, bb.x, s0); s1 = fmaf(sa, bb.y, s1); s2 = fmaf(sa, bb.z, s2); s3 = fmaf(sa, bb.w, s3);
;       s0 = fmaf(vv, kp.x, s0); s1 = fmaf(vv, kp.y, s1); s2 = fmaf(vv, kp.z, s2); s3 = fmaf(vv, kp.w, s3);
;       float y = s0 * rr.x + s1 * rr.y + s2 * rr.z + s3 * rr.w;
;       y = allreduce16(y);
;       if (j == s) ykeep = y;
;       om = om_n; kk = kk_n; bb = bb_n; kp = kp_n; rr = rr_n; vv = vv_n;
;     }
;     Y[(size_t)(rowof(b, c * 16) + j) * 1024 + 256 + h * 64 + rowv] = f2bf(ykeep);
;     if (c + 1 < NCH) lwrite((c + 1) & 1);
;     half_barrier(smem);
	v_pk_mul_f32 v[176:177], v[60:61], v[116:117]
	v_pk_fma_f32 v[176:177], v[58:59], v[118:119], v[176:177]
	s_waitcnt lgkmcnt(4)
	v_pk_fma_f32 v[180:181], v[60:61], v[112:113], v[60:61] neg_lo:[1,0,0] neg_hi:[1,0,0]
	v_add_f32_e32 v178, v176, v177
	v_pk_fma_f32 v[182:183], v[58:59], v[114:115], v[58:59] neg_lo:[1,0,0] neg_hi:[1,0,0]
	s_nop 0
	v_add_f32_dpp v178, v178, v178 quad_perm:[1,0,3,2] row_mask:0xf bank_mask:0xf bound_ctrl:1
	s_waitcnt lgkmcnt(2)
	v_pk_fma_f32 v[180:181], v[132:133], v[124:125], v[180:181] op_sel_hi:[0,1,1]
	v_pk_fma_f32 v[182:183], v[132:133], v[126:127], v[182:183] op_sel_hi:[0,1,1]
	v_add_f32_dpp v178, v178, v178 quad_perm:[2,3,0,1] row_mask:0xf bank_mask:0xf bound_ctrl:1
	v_pk_mul_f32 v[184:185], v[60:61], v[106:107]
	v_pk_fma_f32 v[184:185], v[58:59], v[108:109], v[184:185]
	v_add_f32_dpp v178, v178, v178 row_half_mirror row_mask:0xf bank_mask:0xf bound_ctrl:1
	s_nop 1
	v_add_f32_dpp v178, v178, v178 row_mirror row_mask:0xf bank_mask:0xf bound_ctrl:1
	v_add_f32_e32 v174, v184, v185
	s_waitcnt lgkmcnt(1)
	v_pk_fma_f32 v[60:61], v[178:179], v[120:121], v[180:181] op_sel_hi:[0,1,1] neg_lo:[1,0,0] neg_hi:[1,0,0]
	v_pk_fma_f32 v[58:59], v[178:179], v[122:123], v[182:183] op_sel_hi:[0,1,1] neg_lo:[1,0,0] neg_hi:[1,0,0]
	s_waitcnt lgkmcnt(0)
	v_pk_mul_f32 v[184:185], v[60:61], v[128:129]
	v_pk_fma_f32 v[184:185], v[58:59], v[130:131], v[184:185]
	v_add_f32_e32 v175, v184, v185
	v_add_f32_dpp v160, v160, v160 row_ror:8 row_mask:0xf bank_mask:0x3 bound_ctrl:1
	v_add_f32_dpp v161, v161, v161 row_ror:8 row_mask:0xf bank_mask:0x3 bound_ctrl:1
	v_add_f32_dpp v162, v162, v162 row_ror:8 row_mask:0xf bank_mask:0x3 bound_ctrl:1
	v_add_f32_dpp v163, v163, v163 row_ror:8 row_mask:0xf bank_mask:0x3 bound_ctrl:1
	v_add_f32_dpp v164, v164, v164 row_ror:8 row_mask:0xf bank_mask:0x3 bound_ctrl:1
	v_add_f32_dpp v165, v165, v165 row_ror:8 row_mask:0xf bank_mask:0x3 bound_ctrl:1
	v_add_f32_dpp v166, v166, v166 row_ror:8 row_mask:0xf bank_mask:0x3 bound_ctrl:1
	v_add_f32_dpp v167, v167, v167 row_ror:8 row_mask:0xf bank_mask:0x3 bound_ctrl:1
	v_add_f32_dpp v160, v168, v168 row_ror:8 row_mask:0xf bank_mask:0xc bound_ctrl:1
	v_add_f32_dpp v161, v169, v169 row_ror:8 row_mask:0xf bank_mask:0xc bound_ctrl:1
	v_add_f32_dpp v162, v170, v170 row_ror:8 row_mask:0xf bank_mask:0xc bound_ctrl:1
	v_add_f32_dpp v163, v171, v171 row_ror:8 row_mask:0xf bank_mask:0xc bound_ctrl:1
	v_add_f32_dpp v164, v172, v172 row_ror:8 row_mask:0xf bank_mask:0xc bound_ctrl:1
	v_add_f32_dpp v165, v173, v173 row_ror:8 row_mask:0xf bank_mask:0xc bound_ctrl:1
	v_add_f32_dpp v166, v174, v174 row_ror:8 row_mask:0xf bank_mask:0xc bound_ctrl:1
	v_add_f32_dpp v167, v175, v175 row_ror:8 row_mask:0xf bank_mask:0xc bound_ctrl:1
	v_add_f32_dpp v160, v160, v160 row_half_mirror row_mask:0xf bank_mask:0x5 bound_ctrl:1
	v_add_f32_dpp v161, v161, v161 row_half_mirror row_mask:0xf bank_mask:0x5 bound_ctrl:1
	v_add_f32_dpp v162, v162, v162 row_half_mirror row_mask:0xf bank_mask:0x5 bound_ctrl:1
	v_add_f32_dpp v163, v163, v163 row_half_mirror row_mask:0xf bank_mask:0x5 bound_ctrl:1
	v_add_f32_dpp v160, v164, v164 row_half_mirror row_mask:0xf bank_mask:0xa bound_ctrl:1
	v_add_f32_dpp v161, v165, v165 row_half_mirror row_mask:0xf bank_mask:0xa bound_ctrl:1
	v_add_f32_dpp v162, v166, v166 row_half_mirror row_mask:0xf bank_mask:0xa bound_ctrl:1
	v_add_f32_dpp v163, v167, v167 row_half_mirror row_mask:0xf bank_mask:0xa bound_ctrl:1
	v_and_b32_e32 v186, 2, v76
	v_cmp_ne_u32_e32 vcc, 0, v186
	v_and_b32_e32 v186, 1, v76
	s_nop 0
	v_cndmask_b32_e32 v187, v160, v162, vcc
	v_cndmask_b32_e32 v188, v162, v160, vcc
	v_cndmask_b32_e32 v189, v161, v163, vcc
	v_cndmask_b32_e32 v190, v163, v161, vcc
	v_cmp_ne_u32_e32 vcc, 0, v186
	v_add_f32_dpp v160, v188, v187 quad_perm:[2,3,0,1] row_mask:0xf bank_mask:0xf bound_ctrl:1
	v_add_f32_dpp v161, v190, v189 quad_perm:[2,3,0,1] row_mask:0xf bank_mask:0xf bound_ctrl:1
	v_cndmask_b32_e32 v187, v160, v161, vcc
	v_cndmask_b32_e32 v188, v161, v160, vcc
	s_nop 1
	v_add_f32_dpp v82, v188, v187 quad_perm:[1,0,3,2] row_mask:0xf bank_mask:0xf bound_ctrl:1
	s_lshl_b32 s5, s4, 4
	s_add_i32 s5, s5, s11
	s_cmp_eq_u32 s4, 0
	s_cselect_b32 s5, s10, s5
	v_or_b32_e32 v12, s5, v76
	v_ashrrev_i32_e32 v13, 31, v12
	v_lshlrev_b64 v[12:13], 11, v[12:13]
	v_cvt_pk_bf16_f32 v14, v82, s0
	v_lshl_add_u64 v[12:13], v[56:57], 0, v[12:13]
	global_store_short v[12:13], v14, off
	s_waitcnt lgkmcnt(0)
	s_mov_b64 s[12:13], exec
	s_mov_b64 exec, 1
	ds_add_u32 v193, v195 offset:8
	s_mov_b64 exec, s[12:13]
	v_add_u32_e32 v194, 4, v194
.Lrw_spin:
	ds_read_b32 v196, v193 offset:8
	s_waitcnt lgkmcnt(0)
	v_cmp_lt_u32_e32 vcc, v196, v194
	s_cbranch_vccz .Lrw_bdone
	s_sleep 1
	s_branch .Lrw_spin
.Lrw_bdone:
	s_mov_b32 s4, s28
	s_cmpk_lt_i32 s28, 0x81
	s_cbranch_scc1 .Lrw_head
	s_branch .LBB0_394
